# diff epilogue: the 16 subln-gamma loads issued together; diff slow-path (bias/causal tiles) tail uses the interleaved exp/PV block
# baseline (speedup 1.0000x reference)
; __device__ __forceinline__ float fexp2(float x) { return __builtin_amdgcn_exp2f(x); }
; __device__ __forceinline__ float fmax3(float a, float b, float c) { float d; asm("v_max3_f32 %0, %1, %2, %3" : "=v"(d) : "v"(a), "v"(b), "v"(c)); return d; }
; template <int MODE, int DK, bool PASS2> ...
;     ...
;                         float mx = fmaxf(s0[0], s1[0]);
; #pragma unroll
;                         for (int r = 1; r < 16; ++r) mx = fmax3(mx, s0[r], s1[r]);
;                         mx = xhalf_max(mx);
;                         const float mn = (mx > m_run + 8.0f) ? mx : m_run;
;                         const float alpha = fexp2(m_run - mn);
;                         m_run = mn;
;                         float ps0 = 0.f, ps1 = 0.f;
; #pragma unroll
;                         for (int r = 0; r < 16; ++r) { s0[r] = fexp2(s0[r] - mn); s1[r] = fexp2(s1[r] - mn); ps0 += s0[r]; ps1 += s1[r]; }
;                         l_run = l_run * alpha + (ps0 + ps1);
;                         if (__builtin_amdgcn_ballot_w64(alpha != 1.0f) != 0ull) {
; #pragma unroll
;                             for (int db = 0; db < 4; ++db)
; #pragma unroll
;                                 for (int r = 0; r < 16; ++r) O[db][r] *= alpha;
;                         }
.LBB0_2138:
	s_or_b64 exec, exec, s[28:29]
	s_cmp_eq_u64 s[6:7], 0
	s_cbranch_scc1 .Lslow_diff
	v_max_f32_e32 v92, v98, v98
	v_max_f32_e32 v93, v162, v162
	v_max_f32_e32 v92, v93, v92
	v_max3_f32 v92, v92, v163, v99
	s_nop 0
	v_max3_f32 v92, v92, v160, v100
	s_nop 0
	v_max3_f32 v92, v92, v161, v101
	s_nop 0
	v_max3_f32 v92, v92, v4, v6
	s_nop 0
	v_max3_f32 v92, v92, v5, v7
	s_nop 0
	v_max3_f32 v92, v92, v8, v10
	s_nop 0
	v_max3_f32 v92, v92, v9, v11
	s_nop 0
	v_max3_f32 v92, v92, v12, v14
	s_nop 0
	v_max3_f32 v92, v92, v13, v15
	s_nop 0
	v_max3_f32 v92, v92, v16, v82
	s_nop 0
	v_max3_f32 v92, v92, v17, v83
	s_nop 0
	v_max3_f32 v92, v92, v84, v86
	s_nop 0
	v_max3_f32 v92, v92, v85, v87
	s_nop 0
	v_max3_f32 v92, v92, v88, v90
	s_nop 0
	v_max3_f32 v92, v92, v89, v91
	s_nop 0
	v_mov_b32_e32 v93, v92
	s_nop 1
	v_permlane32_swap_b32_e32 v92, v93
	v_max_f32_e32 v93, v93, v93
	v_max_f32_e32 v92, v92, v92
	v_max_f32_e32 v92, v92, v93
	v_cmp_gt_f32_e32 vcc, v92, v208
	s_nop 1
	v_cndmask_b32_e32 v207, v178, v92, vcc
	v_sub_f32_e32 v92, v178, v207
	v_exp_f32_e32 v92, v92
	s_nop 0
	v_cmp_neq_f32_e32 vcc, 1.0, v92
	s_cbranch_vccz .LBB0_2140
	v_pk_mul_f32 v[80:81], v[80:81], v[92:93] op_sel_hi:[1,0]
	v_pk_mul_f32 v[78:79], v[78:79], v[92:93] op_sel_hi:[1,0]
	v_pk_mul_f32 v[76:77], v[76:77], v[92:93] op_sel_hi:[1,0]
	v_pk_mul_f32 v[74:75], v[74:75], v[92:93] op_sel_hi:[1,0]
	v_pk_mul_f32 v[72:73], v[72:73], v[92:93] op_sel_hi:[1,0]
	v_pk_mul_f32 v[70:71], v[70:71], v[92:93] op_sel_hi:[1,0]
	v_pk_mul_f32 v[68:69], v[68:69], v[92:93] op_sel_hi:[1,0]
	v_pk_mul_f32 v[66:67], v[66:67], v[92:93] op_sel_hi:[1,0]
	v_pk_mul_f32 v[64:65], v[64:65], v[92:93] op_sel_hi:[1,0]
	v_pk_mul_f32 v[62:63], v[62:63], v[92:93] op_sel_hi:[1,0]
	v_pk_mul_f32 v[60:61], v[60:61], v[92:93] op_sel_hi:[1,0]
	v_pk_mul_f32 v[58:59], v[58:59], v[92:93] op_sel_hi:[1,0]
	v_pk_mul_f32 v[56:57], v[56:57], v[92:93] op_sel_hi:[1,0]
	v_pk_mul_f32 v[54:55], v[54:55], v[92:93] op_sel_hi:[1,0]
	v_pk_mul_f32 v[52:53], v[52:53], v[92:93] op_sel_hi:[1,0]
	v_pk_mul_f32 v[50:51], v[50:51], v[92:93] op_sel_hi:[1,0]
	v_pk_mul_f32 v[48:49], v[48:49], v[92:93] op_sel_hi:[1,0]
	v_pk_mul_f32 v[46:47], v[46:47], v[92:93] op_sel_hi:[1,0]
	v_pk_mul_f32 v[44:45], v[44:45], v[92:93] op_sel_hi:[1,0]
	v_pk_mul_f32 v[42:43], v[42:43], v[92:93] op_sel_hi:[1,0]
	v_pk_mul_f32 v[40:41], v[40:41], v[92:93] op_sel_hi:[1,0]
	v_pk_mul_f32 v[38:39], v[38:39], v[92:93] op_sel_hi:[1,0]
	v_pk_mul_f32 v[36:37], v[36:37], v[92:93] op_sel_hi:[1,0]
	v_pk_mul_f32 v[34:35], v[34:35], v[92:93] op_sel_hi:[1,0]
	v_pk_mul_f32 v[32:33], v[32:33], v[92:93] op_sel_hi:[1,0]
	v_pk_mul_f32 v[30:31], v[30:31], v[92:93] op_sel_hi:[1,0]
	v_pk_mul_f32 v[28:29], v[28:29], v[92:93] op_sel_hi:[1,0]
	v_pk_mul_f32 v[26:27], v[26:27], v[92:93] op_sel_hi:[1,0]
	v_pk_mul_f32 v[24:25], v[24:25], v[92:93] op_sel_hi:[1,0]
	v_pk_mul_f32 v[22:23], v[22:23], v[92:93] op_sel_hi:[1,0]
	v_pk_mul_f32 v[20:21], v[20:21], v[92:93] op_sel_hi:[1,0]
	v_pk_mul_f32 v[18:19], v[18:19], v[92:93] op_sel_hi:[1,0]

; #define LAS __attribute__((address_space(3)))
; __device__ __forceinline__ float fexp2(float x) { return __builtin_amdgcn_exp2f(x); }
; __device__ __forceinline__ float fmax3(float a, float b, float c) { float d; asm("v_max3_f32 %0, %1, %2, %3" : "=v"(d) : "v"(a), "v"(b), "v"(c)); return d; }
; template <int MODE, int DK, bool PASS2> ...
;     ...
;                         float mx = fmaxf(s0[0], s1[0]);
; #pragma unroll
;                         for (int r = 1; r < 16; ++r) mx = fmax3(mx, s0[r], s1[r]);
;                         mx = xhalf_max(mx);
;                         const float mn = (mx > m_run + 8.0f) ? mx : m_run;
;                         const float alpha = fexp2(m_run - mn);
;                         m_run = mn;
;                         float ps0 = 0.f, ps1 = 0.f;
; #pragma unroll
;                         for (int r = 0; r < 16; ++r) { s0[r] = fexp2(s0[r] - mn); s1[r] = fexp2(s1[r] - mn); ps0 += s0[r]; ps1 += s1[r]; }
;                         l_run = l_run * alpha + (ps0 + ps1);
;                         if (__builtin_amdgcn_ballot_w64(alpha != 1.0f) != 0ull) {
; #pragma unroll
;                             for (int db = 0; db < 4; ++db)
; #pragma unroll
;                                 for (int r = 0; r < 16; ++r) O[db][r] *= alpha;
;                         }
;     ...
;                     const LAS unsigned char* vb = lds + F_VB0 + buf * F_VBS + ql * 144 + g * 16;
.Lslow_diff:
	s_mul_i32 s98, s58, 0x4800
	v_add_u32_e32 v210, s98, v201
	ds_read_b128 v[212:215], v210 offset:34816
	ds_read_b128 v[216:219], v210 offset:39424
	ds_read_b128 v[220:223], v210 offset:44032
	ds_read_b128 v[224:227], v210 offset:48640
	ds_read_b128 v[228:231], v210 offset:34848
	ds_read_b128 v[232:235], v210 offset:39456
	v_max_f32_e32 v166, v162, v163
	v_max_f32_e32 v167, v98, v99
	v_max3_f32 v166, v166, v160, v161
	v_max3_f32 v167, v167, v100, v101
	v_max3_f32 v166, v166, v4, v5
	v_max3_f32 v167, v167, v6, v7
	v_max3_f32 v166, v166, v8, v9
	v_max3_f32 v167, v167, v10, v11
	v_max3_f32 v166, v166, v12, v13
	v_max3_f32 v167, v167, v14, v15
	v_max3_f32 v166, v166, v16, v17
	v_max3_f32 v167, v167, v82, v83
	v_max3_f32 v166, v166, v84, v85
	v_max3_f32 v167, v167, v86, v87
	v_max3_f32 v166, v166, v88, v89
	v_max3_f32 v167, v167, v90, v91
	v_max_f32_e32 v166, v166, v167
	v_mov_b32_e32 v167, v166
	s_nop 1
	v_permlane32_swap_b32_e32 v166, v167
	v_max_f32_e32 v166, v166, v167
	v_add_f32_e32 v167, 0x41000000, v178
	v_cmp_gt_f32_e32 vcc, v166, v167
	s_nop 1
	v_cndmask_b32_e32 v207, v178, v166, vcc
	v_sub_f32_e32 v167, v178, v207
	v_exp_f32_e32 v178, v167
	s_nop 0
	v_cmp_neq_f32_e32 vcc, 1.0, v178
	s_cbranch_vccz .Lslow_diff_norescale
	v_pk_mul_f32 v[80:81], v[80:81], v[178:179] op_sel_hi:[1,0]
	v_pk_mul_f32 v[78:79], v[78:79], v[178:179] op_sel_hi:[1,0]
	v_pk_mul_f32 v[76:77], v[76:77], v[178:179] op_sel_hi:[1,0]
	v_pk_mul_f32 v[74:75], v[74:75], v[178:179] op_sel_hi:[1,0]
	v_pk_mul_f32 v[72:73], v[72:73], v[178:179] op_sel_hi:[1,0]
	v_pk_mul_f32 v[70:71], v[70:71], v[178:179] op_sel_hi:[1,0]
	v_pk_mul_f32 v[68:69], v[68:69], v[178:179] op_sel_hi:[1,0]
	v_pk_mul_f32 v[66:67], v[66:67], v[178:179] op_sel_hi:[1,0]
	v_pk_mul_f32 v[64:65], v[64:65], v[178:179] op_sel_hi:[1,0]
	v_pk_mul_f32 v[62:63], v[62:63], v[178:179] op_sel_hi:[1,0]
	v_pk_mul_f32 v[60:61], v[60:61], v[178:179] op_sel_hi:[1,0]
	v_pk_mul_f32 v[58:59], v[58:59], v[178:179] op_sel_hi:[1,0]
	v_pk_mul_f32 v[56:57], v[56:57], v[178:179] op_sel_hi:[1,0]
	v_pk_mul_f32 v[54:55], v[54:55], v[178:179] op_sel_hi:[1,0]
	v_pk_mul_f32 v[52:53], v[52:53], v[178:179] op_sel_hi:[1,0]
	v_pk_mul_f32 v[50:51], v[50:51], v[178:179] op_sel_hi:[1,0]
	v_pk_mul_f32 v[48:49], v[48:49], v[178:179] op_sel_hi:[1,0]
	v_pk_mul_f32 v[46:47], v[46:47], v[178:179] op_sel_hi:[1,0]
	v_pk_mul_f32 v[44:45], v[44:45], v[178:179] op_sel_hi:[1,0]
	v_pk_mul_f32 v[42:43], v[42:43], v[178:179] op_sel_hi:[1,0]
	v_pk_mul_f32 v[40:41], v[40:41], v[178:179] op_sel_hi:[1,0]
	v_pk_mul_f32 v[38:39], v[38:39], v[178:179] op_sel_hi:[1,0]
	v_pk_mul_f32 v[36:37], v[36:37], v[178:179] op_sel_hi:[1,0]
	v_pk_mul_f32 v[34:35], v[34:35], v[178:179] op_sel_hi:[1,0]
	v_pk_mul_f32 v[32:33], v[32:33], v[178:179] op_sel_hi:[1,0]
	v_pk_mul_f32 v[30:31], v[30:31], v[178:179] op_sel_hi:[1,0]
	v_pk_mul_f32 v[28:29], v[28:29], v[178:179] op_sel_hi:[1,0]
	v_pk_mul_f32 v[26:27], v[26:27], v[178:179] op_sel_hi:[1,0]
	v_pk_mul_f32 v[24:25], v[24:25], v[178:179] op_sel_hi:[1,0]
	v_pk_mul_f32 v[22:23], v[22:23], v[178:179] op_sel_hi:[1,0]
	v_pk_mul_f32 v[20:21], v[20:21], v[178:179] op_sel_hi:[1,0]
	v_pk_mul_f32 v[18:19], v[18:19], v[178:179] op_sel_hi:[1,0]
; #define LAS __attribute__((address_space(3)))
; __device__ __forceinline__ unsigned pack2(float lo, float hi) { unsigned r; asm volatile("v_cvt_pk_bf16_f32 %0, %1, %2" : "=v"(r) : "v"(lo), "v"(hi)); return r; }
; __device__ __forceinline__ float fexp2(float x) { return __builtin_amdgcn_exp2f(x); }
; __device__ __forceinline__ f32x16 mfma32(bf16x8 a, bf16x8 b, f32x16 c) { return __builtin_amdgcn_mfma_f32_32x32x16_bf16(a, b, c, 0, 0, 0); }
; template <int MODE, int DK, bool PASS2> ...
;     ...
;                         float ps0 = 0.f, ps1 = 0.f;
; #pragma unroll
;                         for (int r = 0; r < 16; ++r) { s0[r] = fexp2(s0[r] - mn); s1[r] = fexp2(s1[r] - mn); ps0 += s0[r]; ps1 += s1[r]; }
;                         l_run = l_run * alpha + (ps0 + ps1);
;     ...
;                 if (!PASS2) {
;                     bf16x8 pf[4];
; #pragma unroll
;                     for (int k2 = 0; k2 < 4; ++k2) {
;                         u32x4 pk;
; #pragma unroll
;                         for (int e = 0; e < 4; ++e) pk[e] = (k2 < 2) ? pack2(s0[(k2 & 1) * 8 + 2 * e], s0[(k2 & 1) * 8 + 2 * e + 1]) : pack2(s1[(k2 & 1) * 8 + 2 * e], s1[(k2 & 1) * 8 + 2 * e + 1]);
;                         pf[k2] = __builtin_bit_cast(bf16x8, pk);
;                     }
;                     const LAS unsigned char* vb = lds + F_VB0 + buf * F_VBS + ql * 144 + g * 16;
;                     __builtin_amdgcn_s_setprio(1);
; #pragma unroll
;                     for (int db = 0; db < 4; ++db)
; #pragma unroll
;                         for (int k2 = 0; k2 < 4; ++k2) {
;                             const bf16x8 vf = *(const LAS bf16x8*)(vb + db * 32 * 144 + k2 * 32);
;                             O[db] = mfma32(vf, pf[k2], O[db]);
;                             if (k2 == 3 && (db & 1)) __builtin_amdgcn_sched_barrier(0);
;                         }
;                     __builtin_amdgcn_s_setprio(0);
.Lslow_diff_norescale:
	v_sub_f32_e32 v110, v162, v207
	v_sub_f32_e32 v111, v163, v207
	v_exp_f32_e32 v102, v110
	v_exp_f32_e32 v103, v111
	v_sub_f32_e32 v112, v160, v207
	v_sub_f32_e32 v113, v161, v207
	v_exp_f32_e32 v104, v112
	v_exp_f32_e32 v105, v113
	v_add_f32_e32 v164, v102, v103
	v_sub_f32_e32 v110, v4, v207
	v_sub_f32_e32 v111, v5, v207
	v_exp_f32_e32 v106, v110
	v_exp_f32_e32 v107, v111
	v_cvt_pk_bf16_f32 v236, v102, v103
	v_add_f32_e32 v164, v164, v104
	v_sub_f32_e32 v112, v8, v207
	v_add_f32_e32 v164, v164, v105
	v_sub_f32_e32 v113, v9, v207
	v_exp_f32_e32 v108, v112
	v_exp_f32_e32 v109, v113
	v_cvt_pk_bf16_f32 v237, v104, v105
	v_add_f32_e32 v164, v164, v106
	v_add_f32_e32 v164, v164, v107
	v_cvt_pk_bf16_f32 v238, v106, v107
	v_add_f32_e32 v164, v164, v108
	v_add_f32_e32 v164, v164, v109
	v_cvt_pk_bf16_f32 v239, v108, v109
	s_setprio 1
	v_sub_f32_e32 v110, v12, v207
	v_sub_f32_e32 v111, v13, v207
	s_waitcnt lgkmcnt(5)
	v_mfma_f32_32x32x16_bf16 v[66:81], v[212:215], v[236:239], v[66:81]
	v_exp_f32_e32 v102, v110
	v_exp_f32_e32 v103, v111
	v_sub_f32_e32 v112, v16, v207
	v_sub_f32_e32 v113, v17, v207
	v_exp_f32_e32 v104, v112
	v_exp_f32_e32 v105, v113
	v_add_f32_e32 v164, v164, v102
	s_waitcnt lgkmcnt(4)
	v_mfma_f32_32x32x16_bf16 v[50:65], v[216:219], v[236:239], v[50:65]
	ds_read_b128 v[212:215], v210 offset:44064
	v_sub_f32_e32 v110, v84, v207
	v_add_f32_e32 v164, v164, v103
	v_sub_f32_e32 v111, v85, v207
	v_exp_f32_e32 v106, v110
	v_exp_f32_e32 v107, v111
	v_cvt_pk_bf16_f32 v240, v102, v103
	v_add_f32_e32 v164, v164, v104
	s_waitcnt lgkmcnt(4)
	v_mfma_f32_32x32x16_bf16 v[34:49], v[220:223], v[236:239], v[34:49]
	ds_read_b128 v[216:219], v210 offset:48672
	v_sub_f32_e32 v112, v88, v207
	v_add_f32_e32 v164, v164, v105
	v_sub_f32_e32 v113, v89, v207
	v_exp_f32_e32 v108, v112
	v_exp_f32_e32 v109, v113
	v_cvt_pk_bf16_f32 v241, v104, v105
	v_add_f32_e32 v164, v164, v106
	s_waitcnt lgkmcnt(4)
	v_mfma_f32_32x32x16_bf16 v[18:33], v[224:227], v[236:239], v[18:33]
	ds_read_b128 v[220:223], v210 offset:34880
	v_add_f32_e32 v164, v164, v107
	v_cvt_pk_bf16_f32 v242, v106, v107
	v_add_f32_e32 v164, v164, v108
	v_add_f32_e32 v164, v164, v109
	v_cvt_pk_bf16_f32 v243, v108, v109
	v_sub_f32_e32 v110, v98, v207
	v_sub_f32_e32 v111, v99, v207
	s_waitcnt lgkmcnt(4)
	v_mfma_f32_32x32x16_bf16 v[66:81], v[228:231], v[240:243], v[66:81]
	ds_read_b128 v[224:227], v210 offset:39488
	v_exp_f32_e32 v102, v110
	v_exp_f32_e32 v103, v111
	v_sub_f32_e32 v112, v100, v207
	v_sub_f32_e32 v113, v101, v207
	v_exp_f32_e32 v104, v112
	v_exp_f32_e32 v105, v113
	v_add_f32_e32 v165, v102, v103
	s_waitcnt lgkmcnt(4)
	v_mfma_f32_32x32x16_bf16 v[50:65], v[232:235], v[240:243], v[50:65]
	ds_read_b128 v[228:231], v210 offset:44096
	v_sub_f32_e32 v110, v6, v207
	v_sub_f32_e32 v111, v7, v207
	v_exp_f32_e32 v106, v110
	v_exp_f32_e32 v107, v111
	v_cvt_pk_bf16_f32 v244, v102, v103
	v_add_f32_e32 v165, v165, v104
	v_sub_f32_e32 v112, v10, v207
	s_waitcnt lgkmcnt(4)
	v_mfma_f32_32x32x16_bf16 v[34:49], v[212:215], v[240:243], v[34:49]
	ds_read_b128 v[232:235], v210 offset:48704
	v_add_f32_e32 v165, v165, v105
	v_sub_f32_e32 v113, v11, v207
	v_exp_f32_e32 v108, v112
	v_exp_f32_e32 v109, v113
	v_cvt_pk_bf16_f32 v245, v104, v105
	v_add_f32_e32 v165, v165, v106
	v_add_f32_e32 v165, v165, v107
	s_waitcnt lgkmcnt(4)
	v_mfma_f32_32x32x16_bf16 v[18:33], v[216:219], v[240:243], v[18:33]
	ds_read_b128 v[212:215], v210 offset:34912
	v_cvt_pk_bf16_f32 v246, v106, v107
	v_add_f32_e32 v165, v165, v108
	v_add_f32_e32 v165, v165, v109
	v_cvt_pk_bf16_f32 v247, v108, v109
	v_sub_f32_e32 v110, v14, v207
	v_sub_f32_e32 v111, v15, v207
	s_waitcnt lgkmcnt(4)
	v_mfma_f32_32x32x16_bf16 v[66:81], v[220:223], v[244:247], v[66:81]
	ds_read_b128 v[216:219], v210 offset:39520
	v_exp_f32_e32 v102, v110
	v_exp_f32_e32 v103, v111
	v_sub_f32_e32 v112, v82, v207
	v_sub_f32_e32 v113, v83, v207
	v_exp_f32_e32 v104, v112
	v_exp_f32_e32 v105, v113
	v_add_f32_e32 v165, v165, v102
	s_waitcnt lgkmcnt(4)
	v_mfma_f32_32x32x16_bf16 v[50:65], v[224:227], v[244:247], v[50:65]
	ds_read_b128 v[220:223], v210 offset:44128
	v_sub_f32_e32 v110, v86, v207
	v_add_f32_e32 v165, v165, v103
	v_sub_f32_e32 v111, v87, v207
	v_exp_f32_e32 v106, v110
	v_exp_f32_e32 v107, v111
	v_cvt_pk_bf16_f32 v248, v102, v103
	v_add_f32_e32 v165, v165, v104
	s_waitcnt lgkmcnt(4)
	v_mfma_f32_32x32x16_bf16 v[34:49], v[228:231], v[244:247], v[34:49]
	ds_read_b128 v[224:227], v210 offset:48736
	v_sub_f32_e32 v112, v90, v207
	v_add_f32_e32 v165, v165, v105
	v_sub_f32_e32 v113, v91, v207
	v_exp_f32_e32 v108, v112
	v_exp_f32_e32 v109, v113
	v_cvt_pk_bf16_f32 v249, v104, v105
	v_add_f32_e32 v165, v165, v106
	s_waitcnt lgkmcnt(4)
	v_mfma_f32_32x32x16_bf16 v[18:33], v[232:235], v[244:247], v[18:33]
	v_add_f32_e32 v165, v165, v107
	v_cvt_pk_bf16_f32 v250, v106, v107
	v_add_f32_e32 v165, v165, v108
	v_add_f32_e32 v165, v165, v109
	v_cvt_pk_bf16_f32 v251, v108, v109
	v_add_f32_e32 v209, v164, v165
	s_waitcnt lgkmcnt(3)
	v_mfma_f32_32x32x16_bf16 v[66:81], v[212:215], v[248:251], v[66:81]
	v_fmac_f32_e32 v209, v206, v178
	s_waitcnt lgkmcnt(2)
	v_mfma_f32_32x32x16_bf16 v[50:65], v[216:219], v[248:251], v[50:65]
	s_waitcnt lgkmcnt(1)
	v_mfma_f32_32x32x16_bf16 v[34:49], v[220:223], v[248:251], v[34:49]
	s_waitcnt lgkmcnt(0)
	v_mfma_f32_32x32x16_bf16 v[18:33], v[224:227], v[248:251], v[18:33]
	s_setprio 0
	s_branch .Lpostpv_diff

; __device__ __forceinline__ unsigned pack2(float lo, float hi) { unsigned r; asm volatile("v_cvt_pk_bf16_f32 %0, %1, %2" : "=v"(r) : "v"(lo), "v"(hi)); return r; }
; __device__ __forceinline__ void diff_item(CPR P, LAS unsigned char* lds, int h, int qb) {
;     ...
;         l += __shfl_xor(l, 32);
;         const float inv = 1.0f / l;
;         if (mp == 0) {
; #pragma unroll
;             for (int db = 0; db < 4; ++db)
; #pragma unroll
;                 for (int r = 0; r < 8; ++r) hold[(db * 8 + r) * 512] = pack2(O[db][2 * r] * inv, O[db][2 * r + 1] * inv);
;         } else {
;             float ss = 0.f;
; #pragma unroll
;             for (int db = 0; db < 4; ++db)
; #pragma unroll
;                 for (int r = 0; r < 8; ++r) {
;                     const unsigned hv = hold[(db * 8 + r) * 512];
;                     const float a = __uint_as_float(hv << 16) - lmbda * (O[db][2 * r] * inv);
;                     const float b = __uint_as_float(hv & 0xffff0000u) - lmbda * (O[db][2 * r + 1] * inv);
;                     O[db][2 * r] = a; O[db][2 * r + 1] = b;
;                     ss += a * a + b * b;
;                 }
.LBB0_2144:
	ds_bpermute_b32 v3, v192, v206
	s_xor_b64 s[20:21], s[20:21], -1
	v_cndmask_b32_e64 v4, 0, 1, s[20:21]
	s_mov_b64 s[6:7], -1
	s_waitcnt lgkmcnt(0)
	v_add_f32_e32 v3, v206, v3
	v_div_scale_f32 v5, s[4:5], v3, v3, 1.0
	v_rcp_f32_e32 v6, v5
	v_cmp_ne_u32_e64 s[4:5], 1, v4
	v_div_scale_f32 v4, vcc, 1.0, v3, 1.0
	v_fma_f32 v7, -v5, v6, 1.0
	v_fmac_f32_e32 v6, v7, v6
	v_mul_f32_e32 v7, v4, v6
	v_fma_f32 v8, -v5, v7, v4
	v_fmac_f32_e32 v7, v8, v6
	v_fma_f32 v4, -v5, v7, v4
	v_div_fmas_f32 v4, v4, v6, v7
	v_div_fixup_f32 v4, v4, v3, 1.0
	s_andn2_b64 vcc, exec, s[20:21]
	v_mul_f32_e32 v3, v66, v4
	v_mul_f32_e32 v82, v67, v4
	v_mul_f32_e32 v5, v68, v4
	v_mul_f32_e32 v83, v69, v4
	v_mul_f32_e32 v66, v70, v4
	v_mul_f32_e32 v84, v71, v4
	v_mul_f32_e32 v67, v72, v4
	v_mul_f32_e32 v72, v73, v4
	v_mul_f32_e32 v68, v74, v4
	v_mul_f32_e32 v73, v75, v4
	v_mul_f32_e32 v69, v76, v4
	v_mul_f32_e32 v74, v77, v4
	v_mul_f32_e32 v70, v78, v4
	v_mul_f32_e32 v75, v79, v4
	v_mul_f32_e32 v71, v80, v4
	v_mul_f32_e32 v76, v81, v4
	v_mul_f32_e32 v50, v50, v4
	v_mul_f32_e32 v77, v51, v4
	v_mul_f32_e32 v51, v52, v4
	v_mul_f32_e32 v78, v53, v4
	v_mul_f32_e32 v52, v54, v4
	v_mul_f32_e32 v79, v55, v4
	v_mul_f32_e32 v53, v56, v4
	v_mul_f32_e32 v80, v57, v4
	v_mul_f32_e32 v54, v58, v4
	v_mul_f32_e32 v81, v59, v4
	v_mul_f32_e32 v55, v60, v4
	v_mul_f32_e32 v85, v61, v4
	v_mul_f32_e32 v56, v62, v4
	v_mul_f32_e32 v62, v63, v4
	v_mul_f32_e32 v57, v64, v4
	v_mul_f32_e32 v63, v65, v4
	v_mul_f32_e32 v58, v34, v4
	v_mul_f32_e32 v64, v35, v4
	v_mul_f32_e32 v59, v36, v4
	v_mul_f32_e32 v65, v37, v4
	v_mul_f32_e32 v60, v38, v4
	v_mul_f32_e32 v86, v39, v4
	v_mul_f32_e32 v61, v40, v4
	v_mul_f32_e32 v87, v41, v4
	v_mul_f32_e32 v42, v42, v4
	v_mul_f32_e32 v88, v43, v4
	v_mul_f32_e32 v43, v44, v4
	v_mul_f32_e32 v44, v45, v4
	s_cbranch_vccnz .LBB0_2146
	ds_read2st64_b32 v[6:7], v194 offset1:8
	global_load_dwordx4 v[90:93], v[156:157], off
	global_load_dwordx4 v[160:163], v[156:157], off offset:32
	global_load_dwordx4 v[164:167], v[156:157], off offset:64
	global_load_dwordx4 v[168:171], v[156:157], off offset:96
	global_load_dwordx4 v[172:175], v[156:157], off offset:128
	global_load_dwordx4 v[208:211], v[156:157], off offset:160
	global_load_dwordx4 v[212:215], v[156:157], off offset:192
	global_load_dwordx4 v[216:219], v[156:157], off offset:224
	global_load_dwordx4 v[220:223], v[156:157], off offset:256
	global_load_dwordx4 v[224:227], v[156:157], off offset:288
	global_load_dwordx4 v[228:231], v[156:157], off offset:320
	global_load_dwordx4 v[232:235], v[156:157], off offset:352
	global_load_dwordx4 v[236:239], v[156:157], off offset:384
	global_load_dwordx4 v[240:243], v[156:157], off offset:416
	global_load_dwordx4 v[244:247], v[156:157], off offset:448
	global_load_dwordx4 v[248:251], v[156:157], off offset:480
	v_mov_b32_e32 v10, v46
	v_mov_b32_e32 v11, v48
	v_pk_mul_f32 v[10:11], v[10:11], v[4:5] op_sel_hi:[1,0]
	s_waitcnt lgkmcnt(0)
	v_lshlrev_b32_e32 v8, 16, v6
	v_and_b32_e32 v6, 0xffff0000, v6
	v_lshlrev_b32_e32 v9, 16, v7
	v_fma_f32 v89, -v144, v82, v6
	v_fma_f32 v96, -v144, v5, v9
	v_and_b32_e32 v9, 0xffff0000, v7
	ds_read2st64_b32 v[6:7], v194 offset0:16 offset1:24
	v_fma_f32 v97, -v144, v83, v9
	v_fma_f32 v45, -v144, v3, v8
	v_mul_f32_e32 v8, v89, v89
	v_mul_f32_e32 v9, v97, v97
	v_fmac_f32_e32 v8, v45, v45
	v_fmac_f32_e32 v9, v96, v96
	v_add_f32_e32 v8, v8, v9
	s_waitcnt lgkmcnt(0)
	v_lshlrev_b32_e32 v9, 16, v6
	v_and_b32_e32 v6, 0xffff0000, v6
	v_fma_f32 v99, -v144, v84, v6
	v_fma_f32 v98, -v144, v66, v9
	v_mul_f32_e32 v6, v99, v99
	v_fmac_f32_e32 v6, v98, v98
	v_add_f32_e32 v8, v8, v6
	v_lshlrev_b32_e32 v6, 16, v7
	v_fma_f32 v100, -v144, v67, v6
	v_and_b32_e32 v9, 0xffff0000, v7
	ds_read2st64_b32 v[6:7], v194 offset0:32 offset1:40
	v_fma_f32 v101, -v144, v72, v9
	v_mul_f32_e32 v9, v101, v101
	v_fmac_f32_e32 v9, v100, v100
	v_add_f32_e32 v8, v8, v9
	s_waitcnt lgkmcnt(0)
	v_lshlrev_b32_e32 v9, 16, v6
	v_and_b32_e32 v6, 0xffff0000, v6
	v_fma_f32 v103, -v144, v73, v6
	v_fma_f32 v102, -v144, v68, v9
	v_mul_f32_e32 v6, v103, v103
	v_fmac_f32_e32 v6, v102, v102
	v_add_f32_e32 v8, v8, v6
	v_lshlrev_b32_e32 v6, 16, v7
	v_fma_f32 v104, -v144, v69, v6
	v_and_b32_e32 v9, 0xffff0000, v7
	ds_read2st64_b32 v[6:7], v194 offset0:48 offset1:56
	v_fma_f32 v105, -v144, v74, v9
	v_mul_f32_e32 v9, v105, v105
	v_fmac_f32_e32 v9, v104, v104
	v_add_f32_e32 v8, v8, v9
	s_waitcnt lgkmcnt(0)
	v_lshlrev_b32_e32 v9, 16, v6
	v_and_b32_e32 v6, 0xffff0000, v6
	v_fma_f32 v107, -v144, v75, v6
	v_fma_f32 v106, -v144, v70, v9
	v_mul_f32_e32 v6, v107, v107
	v_fmac_f32_e32 v6, v106, v106
	v_add_f32_e32 v8, v8, v6
	v_lshlrev_b32_e32 v6, 16, v7
	v_fma_f32 v108, -v144, v71, v6
	v_and_b32_e32 v9, 0xffff0000, v7
	ds_read2st64_b32 v[6:7], v194 offset0:64 offset1:72
	v_fma_f32 v109, -v144, v76, v9
	v_mul_f32_e32 v9, v109, v109
	v_fmac_f32_e32 v9, v108, v108
	v_add_f32_e32 v8, v8, v9
	s_waitcnt lgkmcnt(0)
	v_lshlrev_b32_e32 v9, 16, v6
	v_and_b32_e32 v6, 0xffff0000, v6
	v_fma_f32 v111, -v144, v77, v6
	v_fma_f32 v110, -v144, v50, v9
	v_mul_f32_e32 v6, v111, v111
	v_fmac_f32_e32 v6, v110, v110
	v_add_f32_e32 v8, v8, v6
	v_lshlrev_b32_e32 v6, 16, v7
	v_fma_f32 v112, -v144, v51, v6
	v_and_b32_e32 v9, 0xffff0000, v7
	ds_read2st64_b32 v[6:7], v194 offset0:80 offset1:88
	v_fma_f32 v113, -v144, v78, v9
	v_mul_f32_e32 v9, v113, v113
	v_fmac_f32_e32 v9, v112, v112
	v_add_f32_e32 v8, v8, v9
	s_waitcnt lgkmcnt(0)
	v_lshlrev_b32_e32 v9, 16, v6
	v_and_b32_e32 v6, 0xffff0000, v6
	s_waitcnt vmcnt(19)
; __device__ __forceinline__ void diff_item(CPR P, LAS unsigned char* lds, int h, int qb) {
;     ...
;             float ss = 0.f;
; #pragma unroll
;             for (int db = 0; db < 4; ++db)
; #pragma unroll
;                 for (int r = 0; r < 8; ++r) {
;                     const unsigned hv = hold[(db * 8 + r) * 512];
;                     const float a = __uint_as_float(hv << 16) - lmbda * (O[db][2 * r] * inv);
;                     const float b = __uint_as_float(hv & 0xffff0000u) - lmbda * (O[db][2 * r + 1] * inv);
;                     O[db][2 * r] = a; O[db][2 * r + 1] = b;
;                     ss += a * a + b * b;
;                 }
	v_fma_f32 v115, -v144, v79, v6
	v_fma_f32 v114, -v144, v52, v9
	v_mul_f32_e32 v6, v115, v115
	v_fmac_f32_e32 v6, v114, v114
	v_add_f32_e32 v8, v8, v6
	v_lshlrev_b32_e32 v6, 16, v7
	v_fma_f32 v116, -v144, v53, v6
	v_and_b32_e32 v9, 0xffff0000, v7
	ds_read2st64_b32 v[6:7], v194 offset0:96 offset1:104
	v_fma_f32 v117, -v144, v80, v9
	v_mul_f32_e32 v9, v117, v117
	v_fmac_f32_e32 v9, v116, v116
	v_add_f32_e32 v8, v8, v9
	s_waitcnt lgkmcnt(0)
	v_lshlrev_b32_e32 v9, 16, v6
	v_and_b32_e32 v6, 0xffff0000, v6
	s_waitcnt vmcnt(18)
	v_fma_f32 v119, -v144, v81, v6
	v_fma_f32 v118, -v144, v54, v9
	v_mul_f32_e32 v6, v119, v119
	v_fmac_f32_e32 v6, v118, v118
	v_add_f32_e32 v8, v8, v6
	v_lshlrev_b32_e32 v6, 16, v7
	v_fma_f32 v120, -v144, v55, v6
	v_and_b32_e32 v9, 0xffff0000, v7
	ds_read2st64_b32 v[6:7], v194 offset0:112 offset1:120
	v_fma_f32 v121, -v144, v85, v9
	v_mul_f32_e32 v9, v121, v121
	v_fmac_f32_e32 v9, v120, v120
	v_add_f32_e32 v8, v8, v9
	s_waitcnt lgkmcnt(0)
	v_lshlrev_b32_e32 v9, 16, v6
	v_and_b32_e32 v6, 0xffff0000, v6
	s_waitcnt vmcnt(17)
	v_fma_f32 v123, -v144, v62, v6
	v_fma_f32 v122, -v144, v56, v9
	v_mul_f32_e32 v6, v123, v123
	v_fmac_f32_e32 v6, v122, v122
	v_add_f32_e32 v8, v8, v6
	v_lshlrev_b32_e32 v6, 16, v7
	v_fma_f32 v124, -v144, v57, v6
	v_and_b32_e32 v9, 0xffff0000, v7
	ds_read2st64_b32 v[6:7], v194 offset0:128 offset1:136
	v_fma_f32 v125, -v144, v63, v9
	v_mul_f32_e32 v9, v125, v125
	v_fmac_f32_e32 v9, v124, v124
	v_add_f32_e32 v8, v8, v9
	s_waitcnt lgkmcnt(0)
	v_lshlrev_b32_e32 v9, 16, v6
	v_and_b32_e32 v6, 0xffff0000, v6
	s_waitcnt vmcnt(16)
	v_fma_f32 v127, -v144, v64, v6
	v_fma_f32 v126, -v144, v58, v9
	v_mul_f32_e32 v6, v127, v127
	v_fmac_f32_e32 v6, v126, v126
	v_add_f32_e32 v8, v8, v6
	v_lshlrev_b32_e32 v6, 16, v7
	v_fma_f32 v128, -v144, v59, v6
	v_and_b32_e32 v9, 0xffff0000, v7
	ds_read2st64_b32 v[6:7], v194 offset0:144 offset1:152
	v_fma_f32 v129, -v144, v65, v9
	v_mul_f32_e32 v9, v129, v129
	v_fmac_f32_e32 v9, v128, v128
	v_add_f32_e32 v8, v8, v9
	s_waitcnt lgkmcnt(0)
	v_lshlrev_b32_e32 v9, 16, v6
	v_and_b32_e32 v6, 0xffff0000, v6
	v_fma_f32 v131, -v144, v86, v6
	v_fma_f32 v130, -v144, v60, v9
	v_mul_f32_e32 v6, v131, v131
	v_fmac_f32_e32 v6, v130, v130
	v_add_f32_e32 v8, v8, v6
	v_lshlrev_b32_e32 v6, 16, v7
	v_fma_f32 v132, -v144, v61, v6
	v_and_b32_e32 v9, 0xffff0000, v7
	ds_read2st64_b32 v[6:7], v194 offset0:160 offset1:168
	v_fma_f32 v133, -v144, v87, v9
	v_mul_f32_e32 v9, v133, v133
	v_fmac_f32_e32 v9, v132, v132
	v_add_f32_e32 v8, v8, v9
	s_waitcnt lgkmcnt(0)
	v_lshlrev_b32_e32 v9, 16, v6
	v_and_b32_e32 v6, 0xffff0000, v6
	v_fma_f32 v135, -v144, v88, v6
	v_fma_f32 v134, -v144, v42, v9
	v_mul_f32_e32 v6, v135, v135
	v_fmac_f32_e32 v6, v134, v134
	v_add_f32_e32 v6, v8, v6
	v_lshlrev_b32_e32 v8, 16, v7
	v_fma_f32 v136, -v144, v43, v8
	ds_read2st64_b32 v[8:9], v194 offset0:176 offset1:184
	v_and_b32_e32 v7, 0xffff0000, v7
	v_fma_f32 v137, -v144, v44, v7
	v_mul_f32_e32 v7, v137, v137
	v_fmac_f32_e32 v7, v136, v136
	v_add_f32_e32 v14, v6, v7
	s_waitcnt lgkmcnt(0)
	v_lshlrev_b32_e32 v7, 16, v9
	v_lshlrev_b32_e32 v6, 16, v8
	v_pk_fma_f32 v[6:7], v[144:145], v[10:11], v[6:7] neg_lo:[1,0,0] neg_hi:[1,0,0]
	v_mov_b32_e32 v10, v47
	v_mov_b32_e32 v11, v49
	v_and_b32_e32 v9, 0xffff0000, v9
	v_and_b32_e32 v8, 0xffff0000, v8
	v_pk_mul_f32 v[10:11], v[10:11], v[4:5] op_sel_hi:[1,0]
	ds_read2st64_b32 v[12:13], v194 offset0:192 offset1:200
	v_pk_fma_f32 v[8:9], v[144:145], v[10:11], v[8:9] neg_lo:[1,0,0] neg_hi:[1,0,0]
	v_mov_b32_e32 v15, v20
	v_pk_mul_f32 v[10:11], v[8:9], v[8:9]
	v_mov_b32_e32 v17, v24
	v_pk_fma_f32 v[10:11], v[6:7], v[6:7], v[10:11]
	v_mov_b32_e32 v39, v28
	v_add_f32_e32 v10, v14, v10
	v_mov_b32_e32 v14, v18
	v_add_f32_e32 v16, v10, v11
	s_waitcnt lgkmcnt(0)
	v_lshlrev_b32_e32 v11, 16, v13
	v_lshlrev_b32_e32 v10, 16, v12
	v_pk_mul_f32 v[14:15], v[14:15], v[4:5] op_sel_hi:[1,0]
	v_and_b32_e32 v13, 0xffff0000, v13
	v_pk_fma_f32 v[10:11], v[144:145], v[14:15], v[10:11] neg_lo:[1,0,0] neg_hi:[1,0,0]
	v_mov_b32_e32 v14, v19
	v_mov_b32_e32 v15, v21
	v_and_b32_e32 v12, 0xffff0000, v12
	v_pk_mul_f32 v[14:15], v[14:15], v[4:5] op_sel_hi:[1,0]
	ds_read2st64_b32 v[40:41], v194 offset0:240 offset1:248
	v_pk_fma_f32 v[34:35], v[144:145], v[14:15], v[12:13] neg_lo:[1,0,0] neg_hi:[1,0,0]
	ds_read2st64_b32 v[14:15], v194 offset0:208 offset1:216
	v_pk_mul_f32 v[12:13], v[34:35], v[34:35]
	v_mov_b32_e32 v95, v32
	v_pk_fma_f32 v[12:13], v[10:11], v[10:11], v[12:13]
	s_nop 0
	v_add_f32_e32 v12, v16, v12
	v_mov_b32_e32 v16, v22
	v_add_f32_e32 v38, v12, v13
	s_waitcnt lgkmcnt(0)
	v_lshlrev_b32_e32 v13, 16, v15
	v_lshlrev_b32_e32 v12, 16, v14
	v_pk_mul_f32 v[16:17], v[16:17], v[4:5] op_sel_hi:[1,0]
	v_and_b32_e32 v15, 0xffff0000, v15
	v_pk_fma_f32 v[12:13], v[144:145], v[16:17], v[12:13] neg_lo:[1,0,0] neg_hi:[1,0,0]
	v_mov_b32_e32 v16, v23
	v_mov_b32_e32 v17, v25
	v_and_b32_e32 v14, 0xffff0000, v14
	v_pk_mul_f32 v[16:17], v[16:17], v[4:5] op_sel_hi:[1,0]
	s_nop 0
	v_pk_fma_f32 v[36:37], v[144:145], v[16:17], v[14:15] neg_lo:[1,0,0] neg_hi:[1,0,0]
	ds_read2st64_b32 v[16:17], v194 offset0:224 offset1:232
	v_pk_mul_f32 v[14:15], v[36:37], v[36:37]
	s_nop 0
	v_pk_fma_f32 v[14:15], v[12:13], v[12:13], v[14:15]
	s_nop 0
	v_add_f32_e32 v14, v38, v14
	v_mov_b32_e32 v38, v26
	v_add_f32_e32 v94, v14, v15
	s_waitcnt lgkmcnt(0)
; __device__ __forceinline__ void diff_item(CPR P, LAS unsigned char* lds, int h, int qb) {
;     ...
;                 for (int r = 0; r < 8; ++r) {
;                     const unsigned hv = hold[(db * 8 + r) * 512];
;                     const float a = __uint_as_float(hv << 16) - lmbda * (O[db][2 * r] * inv);
;                     const float b = __uint_as_float(hv & 0xffff0000u) - lmbda * (O[db][2 * r + 1] * inv);
;                     O[db][2 * r] = a; O[db][2 * r + 1] = b;
;                     ss += a * a + b * b;
;                 }
;             ss += __shfl_xor(ss, 32);
;             const float rn = rsqrtf(ss * (1.0f / 128.0f) + EPS) * (1.0f - LINIT);
	v_lshlrev_b32_e32 v15, 16, v17
	v_lshlrev_b32_e32 v14, 16, v16
	v_pk_mul_f32 v[38:39], v[38:39], v[4:5] op_sel_hi:[1,0]
	v_and_b32_e32 v17, 0xffff0000, v17
	v_pk_fma_f32 v[14:15], v[144:145], v[38:39], v[14:15] neg_lo:[1,0,0] neg_hi:[1,0,0]
	v_mov_b32_e32 v38, v27
	v_mov_b32_e32 v39, v29
	v_and_b32_e32 v16, 0xffff0000, v16
	v_pk_mul_f32 v[38:39], v[38:39], v[4:5] op_sel_hi:[1,0]
	s_nop 0
	v_pk_fma_f32 v[38:39], v[144:145], v[38:39], v[16:17] neg_lo:[1,0,0] neg_hi:[1,0,0]
	s_nop 0
	v_pk_mul_f32 v[16:17], v[38:39], v[38:39]
	s_nop 0
	v_pk_fma_f32 v[16:17], v[14:15], v[14:15], v[16:17]
	s_nop 0
	v_add_f32_e32 v16, v94, v16
	v_mov_b32_e32 v94, v30
	v_add_f32_e32 v138, v16, v17
	v_lshlrev_b32_e32 v17, 16, v41
	v_lshlrev_b32_e32 v16, 16, v40
	v_pk_mul_f32 v[94:95], v[94:95], v[4:5] op_sel_hi:[1,0]
	v_and_b32_e32 v41, 0xffff0000, v41
	v_pk_fma_f32 v[16:17], v[144:145], v[94:95], v[16:17] neg_lo:[1,0,0] neg_hi:[1,0,0]
	v_mov_b32_e32 v94, v31
	v_mov_b32_e32 v95, v33
	v_and_b32_e32 v40, 0xffff0000, v40
	v_pk_mul_f32 v[94:95], v[94:95], v[4:5] op_sel_hi:[1,0]
	s_nop 0
	v_pk_fma_f32 v[40:41], v[144:145], v[94:95], v[40:41] neg_lo:[1,0,0] neg_hi:[1,0,0]
	s_nop 0
	v_pk_mul_f32 v[94:95], v[40:41], v[40:41]
	s_nop 0
	v_pk_fma_f32 v[94:95], v[16:17], v[16:17], v[94:95]
	s_nop 0
	v_add_f32_e32 v94, v138, v94
	v_add_f32_e32 v94, v94, v95
	ds_bpermute_b32 v95, v192, v94
	s_waitcnt lgkmcnt(0)
	v_add_f32_e32 v94, v94, v95
	v_fmamk_f32 v94, v94, 0x3c000000, v187
	v_mul_f32_e32 v95, 0x4b800000, v94
	v_cmp_gt_f32_e32 vcc, s37, v94
	s_nop 1
	v_cndmask_b32_e32 v94, v94, v95, vcc
	v_rsq_f32_e32 v94, v94
	s_nop 0
	v_mul_f32_e32 v95, 0x45800000, v94
	v_cndmask_b32_e32 v94, v94, v95, vcc
	v_mul_f32_e32 v94, 0x3f24fd5c, v94
	v_mul_f32_e32 v45, v45, v94
	s_waitcnt vmcnt(0)
; __device__ __forceinline__ void st_bf4(bfraw* p, f32x4 v) { u32x2 o; o[0] = pack2(v[0], v[1]); o[1] = pack2(v[2], v[3]); *(u32x2*)p = o; }
; __device__ __forceinline__ void diff_item(CPR P, LAS unsigned char* lds, int h, int qb) {
;     ...
;             const float* sg = P.in[10];
;             bfraw* orow = mix + (size_t)t * DM + h * 128 + 4 * g;
; #pragma unroll
;             for (int db = 0; db < 4; ++db)
; #pragma unroll
;                 for (int r4 = 0; r4 < 4; ++r4) {
;                     const f32x4 gv = *(const f32x4*)(sg + db * 32 + r4 * 8 + 4 * g);
;                     f32x4 v;
; #pragma unroll
;                     for (int e = 0; e < 4; ++e) v[e] = O[db][r4 * 4 + e] * rn * gv[e];
;                     st_bf4(orow + db * 32 + r4 * 8, v);
;                 }
	v_mul_f32_e32 v45, v90, v45
	v_mul_f32_e32 v89, v89, v94
	v_mul_f32_e32 v90, v96, v94
	v_mul_f32_e32 v89, v91, v89
	v_mul_f32_e32 v91, v92, v90
	v_mul_f32_e32 v90, v97, v94
	v_mul_f32_e32 v92, v93, v90
	v_cvt_pk_bf16_f32 v90, v45, v89
	v_cvt_pk_bf16_f32 v91, v91, v92
	global_store_dwordx2 v[154:155], v[90:91], off
	v_mul_f32_e32 v45, v98, v94
	v_mul_f32_e32 v89, v99, v94
	v_mul_f32_e32 v95, v108, v94
	v_mul_f32_e32 v96, v109, v94
	v_mul_f32_e32 v6, v6, v94
	v_mul_f32_e32 v7, v7, v94
	v_mul_f32_e32 v8, v8, v94
	v_mul_f32_e32 v9, v9, v94
	v_mul_f32_e32 v10, v10, v94
	v_mul_f32_e32 v34, v34, v94
	v_mul_f32_e32 v11, v11, v94
	v_mul_f32_e32 v35, v35, v94
	v_mul_f32_e32 v45, v160, v45
	v_mul_f32_e32 v90, v100, v94
	v_mul_f32_e32 v89, v161, v89
	v_mul_f32_e32 v91, v162, v90
	v_mul_f32_e32 v90, v101, v94
	v_mul_f32_e32 v92, v163, v90
	v_cvt_pk_bf16_f32 v90, v45, v89
	v_cvt_pk_bf16_f32 v91, v91, v92
	global_store_dwordx2 v[154:155], v[90:91], off offset:16
	v_mul_f32_e32 v45, v102, v94
	v_mul_f32_e32 v89, v103, v94
	v_mul_f32_e32 v45, v164, v45
	v_mul_f32_e32 v90, v104, v94
	v_mul_f32_e32 v89, v165, v89
	v_mul_f32_e32 v91, v166, v90
	v_mul_f32_e32 v90, v105, v94
	v_mul_f32_e32 v92, v167, v90
	v_cvt_pk_bf16_f32 v90, v45, v89
	v_cvt_pk_bf16_f32 v91, v91, v92
	global_store_dwordx2 v[154:155], v[90:91], off offset:32
	v_mul_f32_e32 v89, v107, v94
	v_mul_f32_e32 v45, v106, v94
	v_mul_f32_e32 v89, v169, v89
	v_mul_f32_e32 v91, v170, v95
	v_mul_f32_e32 v45, v168, v45
	v_mul_f32_e32 v92, v171, v96
	v_cvt_pk_bf16_f32 v90, v45, v89
	v_cvt_pk_bf16_f32 v91, v91, v92
	global_store_dwordx2 v[154:155], v[90:91], off offset:48
	v_mul_f32_e32 v89, v111, v94
	v_mul_f32_e32 v95, v112, v94
	v_mul_f32_e32 v45, v110, v94
	v_mul_f32_e32 v96, v113, v94
	v_mul_f32_e32 v89, v89, v173
	v_mul_f32_e32 v91, v95, v174
	v_mul_f32_e32 v45, v45, v172
	v_mul_f32_e32 v92, v96, v175
	v_cvt_pk_bf16_f32 v90, v45, v89
	v_cvt_pk_bf16_f32 v91, v91, v92
	global_store_dwordx2 v[154:155], v[90:91], off offset:64
	v_mul_f32_e32 v89, v115, v94
	v_mul_f32_e32 v95, v116, v94
	v_mul_f32_e32 v45, v114, v94
	v_mul_f32_e32 v96, v117, v94
	v_mul_f32_e32 v89, v89, v209
	v_mul_f32_e32 v91, v95, v210
	v_mul_f32_e32 v45, v45, v208
	v_mul_f32_e32 v92, v96, v211
	v_cvt_pk_bf16_f32 v90, v45, v89
	v_cvt_pk_bf16_f32 v91, v91, v92
	global_store_dwordx2 v[154:155], v[90:91], off offset:80
	v_mul_f32_e32 v89, v119, v94
	v_mul_f32_e32 v95, v120, v94
	v_mul_f32_e32 v45, v118, v94
	v_mul_f32_e32 v96, v121, v94
	v_mul_f32_e32 v89, v89, v213
	v_mul_f32_e32 v91, v95, v214
	v_mul_f32_e32 v45, v45, v212
	v_mul_f32_e32 v92, v96, v215
	v_cvt_pk_bf16_f32 v90, v45, v89
	v_cvt_pk_bf16_f32 v91, v91, v92
	global_store_dwordx2 v[154:155], v[90:91], off offset:96
	v_mul_f32_e32 v89, v123, v94
	v_mul_f32_e32 v95, v124, v94
	v_mul_f32_e32 v45, v122, v94
	v_mul_f32_e32 v96, v125, v94
	v_mul_f32_e32 v89, v89, v217
	v_mul_f32_e32 v91, v95, v218
	v_mul_f32_e32 v45, v45, v216
	v_mul_f32_e32 v92, v96, v219
	v_cvt_pk_bf16_f32 v90, v45, v89
	v_cvt_pk_bf16_f32 v91, v91, v92
	global_store_dwordx2 v[154:155], v[90:91], off offset:112
	v_mul_f32_e32 v89, v127, v94
	v_mul_f32_e32 v95, v128, v94
	v_mul_f32_e32 v45, v126, v94
	v_mul_f32_e32 v96, v129, v94
	v_mul_f32_e32 v89, v89, v221
	v_mul_f32_e32 v91, v95, v222
	v_mul_f32_e32 v45, v45, v220
	v_mul_f32_e32 v92, v96, v223
	v_cvt_pk_bf16_f32 v90, v45, v89
	v_cvt_pk_bf16_f32 v91, v91, v92
	global_store_dwordx2 v[154:155], v[90:91], off offset:128
	v_mul_f32_e32 v89, v131, v94
	v_mul_f32_e32 v95, v132, v94
	v_mul_f32_e32 v45, v130, v94
	v_mul_f32_e32 v96, v133, v94
	v_mul_f32_e32 v89, v89, v225
	v_mul_f32_e32 v91, v95, v226
	v_mul_f32_e32 v45, v45, v224
	v_mul_f32_e32 v92, v96, v227
	v_cvt_pk_bf16_f32 v90, v45, v89
	v_cvt_pk_bf16_f32 v91, v91, v92
	global_store_dwordx2 v[154:155], v[90:91], off offset:144
	v_mul_f32_e32 v89, v135, v94
	v_mul_f32_e32 v95, v136, v94
	v_mul_f32_e32 v45, v134, v94
	v_mul_f32_e32 v96, v137, v94
	v_mul_f32_e32 v89, v89, v229
	v_mul_f32_e32 v91, v95, v230
	v_mul_f32_e32 v45, v45, v228
	v_mul_f32_e32 v92, v96, v231
	v_cvt_pk_bf16_f32 v90, v45, v89
	v_cvt_pk_bf16_f32 v91, v91, v92
	global_store_dwordx2 v[154:155], v[90:91], off offset:160
	v_mul_f32_e32 v6, v6, v232
	v_mul_f32_e32 v7, v7, v234
	v_mul_f32_e32 v8, v8, v233
	v_mul_f32_e32 v9, v9, v235
	v_cvt_pk_bf16_f32 v6, v6, v8
	v_cvt_pk_bf16_f32 v7, v7, v9
	global_store_dwordx2 v[154:155], v[6:7], off offset:176
	v_mul_f32_e32 v6, v10, v236
	v_mul_f32_e32 v7, v34, v237
	v_mul_f32_e32 v8, v11, v238
	v_mul_f32_e32 v9, v35, v239
	v_cvt_pk_bf16_f32 v6, v6, v7
	v_cvt_pk_bf16_f32 v7, v8, v9
	global_store_dwordx2 v[154:155], v[6:7], off offset:192
	v_mul_f32_e32 v10, v12, v94
	v_mul_f32_e32 v11, v36, v94
	v_mul_f32_e32 v12, v13, v94
	v_mul_f32_e32 v13, v37, v94
	v_mul_f32_e32 v6, v10, v240
	v_mul_f32_e32 v7, v11, v241
	v_mul_f32_e32 v8, v12, v242
	v_mul_f32_e32 v9, v13, v243
	v_cvt_pk_bf16_f32 v6, v6, v7
	v_cvt_pk_bf16_f32 v7, v8, v9
	global_store_dwordx2 v[154:155], v[6:7], off offset:208
	v_mul_f32_e32 v10, v14, v94
	v_mul_f32_e32 v11, v38, v94
	v_mul_f32_e32 v12, v15, v94
	v_mul_f32_e32 v13, v39, v94
	v_mul_f32_e32 v6, v10, v244
	v_mul_f32_e32 v7, v11, v245
	v_mul_f32_e32 v8, v12, v246
	v_mul_f32_e32 v9, v13, v247
	v_cvt_pk_bf16_f32 v6, v6, v7
	v_cvt_pk_bf16_f32 v7, v8, v9
	global_store_dwordx2 v[154:155], v[6:7], off offset:224
	v_mul_f32_e32 v10, v16, v94
	v_mul_f32_e32 v11, v40, v94
	v_mul_f32_e32 v12, v17, v94
	v_mul_f32_e32 v13, v41, v94
	v_mul_f32_e32 v6, v10, v248
	v_mul_f32_e32 v7, v11, v249
	v_mul_f32_e32 v8, v12, v250
	v_mul_f32_e32 v9, v13, v251
	v_cvt_pk_bf16_f32 v6, v6, v7
	v_cvt_pk_bf16_f32 v7, v8, v9
	global_store_dwordx2 v[154:155], v[6:7], off offset:240
	s_cbranch_execnz .LBB0_2123
	s_branch .LBB0_2147
